# gMLP mixing phase: per-group global loads hoisted into prefetch blocks (one batched wait instead of 28 serialized round trips), on top of attention reschedule + EpiRes epilogue
# speedup vs baseline: 1.0093x; 1.0093x over previous
.LBB0_296:
	v_lshl_add_u64 v[0:1], v[154:155], 0, s[76:77]
	global_load_dwordx4 v[180:183], v[0:1], off
	v_lshl_add_u64 v[0:1], v[146:147], 0, s[76:77]
	global_load_dwordx4 v[188:191], v[0:1], off
	v_lshl_add_u64 v[0:1], v[148:149], 0, s[76:77]
	global_load_dwordx4 v[192:195], v[0:1], off
	v_lshl_add_u64 v[0:1], v[150:151], 0, s[76:77]
	global_load_dwordx4 v[202:205], v[0:1], off
	v_lshl_add_u64 v[0:1], v[144:145], 0, s[76:77]
	global_load_dwordx4 v[206:209], v[0:1], off
	v_lshl_add_u64 v[0:1], v[98:99], 0, s[0:1]
	global_load_dword v26, v[0:1], off
	v_lshl_add_u64 v[0:1], v[100:101], 0, s[0:1]
	global_load_dword v27, v[0:1], off
	v_lshl_add_u64 v[0:1], v[142:143], 0, s[76:77]
	global_load_dwordx4 v[210:213], v[0:1], off
	v_lshl_add_u64 v[0:1], v[92:93], 0, s[0:1]
	global_load_dword v28, v[0:1], off
	v_lshl_add_u64 v[0:1], v[94:95], 0, s[0:1]
	global_load_dword v29, v[0:1], off
	v_lshl_add_u64 v[0:1], v[140:141], 0, s[76:77]
	global_load_dwordx4 v[214:217], v[0:1], off
	v_lshl_add_u64 v[0:1], v[86:87], 0, s[0:1]
	global_load_dword v30, v[0:1], off
	v_lshl_add_u64 v[0:1], v[88:89], 0, s[0:1]
	global_load_dword v31, v[0:1], off
	v_lshl_add_u64 v[0:1], v[138:139], 0, s[76:77]
	global_load_dwordx4 v[218:221], v[0:1], off
	v_lshl_add_u64 v[0:1], v[80:81], 0, s[0:1]
	global_load_dword v238, v[0:1], off
	v_lshl_add_u64 v[0:1], v[82:83], 0, s[0:1]
	global_load_dword v239, v[0:1], off
	v_lshl_add_u64 v[0:1], v[136:137], 0, s[76:77]
	global_load_dwordx4 v[222:225], v[0:1], off
	v_lshl_add_u64 v[0:1], v[74:75], 0, s[0:1]
	global_load_dword v240, v[0:1], off
	v_lshl_add_u64 v[0:1], v[76:77], 0, s[0:1]
	global_load_dword v241, v[0:1], off
	v_lshl_add_u64 v[0:1], v[134:135], 0, s[76:77]
	global_load_dwordx4 v[226:229], v[0:1], off
	v_lshl_add_u64 v[0:1], v[68:69], 0, s[0:1]
	global_load_dword v247, v[0:1], off
	v_lshl_add_u64 v[0:1], v[70:71], 0, s[0:1]
	global_load_dword v248, v[0:1], off
	v_lshl_add_u64 v[0:1], v[132:133], 0, s[76:77]
	global_load_dwordx4 v[230:233], v[0:1], off
	v_lshl_add_u64 v[0:1], v[62:63], 0, s[0:1]
	global_load_dword v249, v[0:1], off
	v_lshl_add_u64 v[0:1], v[64:65], 0, s[0:1]
	global_load_dword v250, v[0:1], off
	v_lshl_add_u64 v[0:1], v[130:131], 0, s[76:77]
	global_load_dwordx4 v[234:237], v[0:1], off
	v_lshl_add_u64 v[0:1], v[56:57], 0, s[0:1]
	global_load_dword v251, v[0:1], off
	v_lshl_add_u64 v[0:1], v[58:59], 0, s[0:1]
	global_load_dword v252, v[0:1], off
	global_load_dword v196, v[152:153], off
	global_load_dword v197, v[152:153], off offset:64
	global_load_dword v198, v[152:153], off offset:128
	global_load_dword v201, v[152:153], off offset:192
	global_load_dword v245, v[152:153], off offset:256
	global_load_dword v246, v[152:153], off offset:320
	global_load_dword v253, v[152:153], off offset:384
	global_load_dword v254, v[152:153], off offset:448
	s_waitcnt vmcnt(0)
	v_lshl_add_u64 v[0:1], v[154:155], 0, s[76:77]
	v_mov_b32_e32 v0, v180
	v_mov_b32_e32 v1, v181
	v_mov_b32_e32 v2, v182
	v_mov_b32_e32 v3, v183
	v_add_u32_e32 v4, v157, v159
	s_mov_b64 s[2:3], 0x200
	v_lshl_add_u64 v[154:155], v[154:155], 0, s[84:85]
	s_waitcnt vmcnt(0)
	ds_write_b128 v4, v[0:3]
	v_lshl_add_u64 v[0:1], v[146:147], 0, s[76:77]
	v_mov_b32_e32 v0, v188
	v_mov_b32_e32 v1, v189
	v_mov_b32_e32 v2, v190
	v_mov_b32_e32 v3, v191
	v_add_u32_e32 v4, v157, v160
	v_lshl_add_u64 v[146:147], v[146:147], 0, s[84:85]
	s_waitcnt vmcnt(0)
	ds_write_b128 v4, v[0:3]
	v_lshl_add_u64 v[0:1], v[148:149], 0, s[76:77]
	v_mov_b32_e32 v0, v192
	v_mov_b32_e32 v1, v193
	v_mov_b32_e32 v2, v194
	v_mov_b32_e32 v3, v195
	v_add_u32_e32 v4, v157, v161
	v_lshl_add_u64 v[148:149], v[148:149], 0, s[84:85]
	s_waitcnt vmcnt(0)
	ds_write_b128 v4, v[0:3]
	v_lshl_add_u64 v[0:1], v[150:151], 0, s[76:77]
	v_mov_b32_e32 v0, v202
	v_mov_b32_e32 v1, v203
	v_mov_b32_e32 v2, v204
	v_mov_b32_e32 v3, v205
	v_add_u32_e32 v4, v157, v162
	v_lshl_add_u64 v[150:151], v[150:151], 0, s[84:85]
	s_waitcnt vmcnt(0)
	ds_write_b128 v4, v[0:3]
	v_lshl_add_u64 v[0:1], v[144:145], 0, s[76:77]
	v_mov_b32_e32 v0, v206
	v_mov_b32_e32 v1, v207
	v_mov_b32_e32 v2, v208
	v_mov_b32_e32 v3, v209
	v_lshl_add_u64 v[4:5], v[98:99], 0, s[0:1]
	v_mov_b32_e32 v16, v26
	v_lshl_add_u64 v[4:5], v[100:101], 0, s[0:1]
	v_mov_b32_e32 v17, v27
	v_lshl_add_u64 v[144:145], v[144:145], 0, s[88:89]
	s_waitcnt vmcnt(2)
	v_lshlrev_b32_e32 v18, 16, v0
	v_and_b32_e32 v19, 0xffff0000, v0
	v_lshlrev_b32_e32 v20, 16, v1
	v_and_b32_e32 v21, 0xffff0000, v1
	v_lshlrev_b32_e32 v22, 16, v2
	v_and_b32_e32 v23, 0xffff0000, v2
	v_lshlrev_b32_e32 v24, 16, v3
	v_and_b32_e32 v25, 0xffff0000, v3
	ds_read_b128 v[0:3], v171
	ds_read_b128 v[4:7], v171 offset:16
	ds_read_b128 v[8:11], v171 offset:32
	ds_read_b128 v[12:15], v171 offset:48
	s_waitcnt lgkmcnt(3)
	v_sub_f32_e32 v0, v18, v0
	v_mul_f32_e32 v0, v1, v0
	v_sub_f32_e32 v1, v19, v2
	s_waitcnt lgkmcnt(2)
	v_sub_f32_e32 v2, v20, v4
	s_waitcnt lgkmcnt(1)
	v_sub_f32_e32 v4, v22, v8
	v_mul_f32_e32 v1, v3, v1
	v_mul_f32_e32 v2, v5, v2
	v_sub_f32_e32 v3, v21, v6
	v_mul_f32_e32 v4, v9, v4
	v_sub_f32_e32 v5, v23, v10
	s_waitcnt vmcnt(0)
	v_fma_f32 v0, v16, v0, v17
	v_fma_f32 v1, v16, v1, v17
	v_fma_f32 v2, v16, v2, v17
	v_mul_f32_e32 v3, v7, v3
	v_fma_f32 v4, v16, v4, v17
	v_mul_f32_e32 v5, v11, v5
	s_waitcnt lgkmcnt(0)
	v_sub_f32_e32 v6, v24, v12
	v_sub_f32_e32 v7, v25, v14
	v_fma_f32 v3, v16, v3, v17
	v_fma_f32 v5, v16, v5, v17
	v_mul_f32_e32 v6, v13, v6
	v_mul_f32_e32 v7, v15, v7
	v_cvt_pk_bf16_f32 v0, v0, v1
	v_cvt_pk_bf16_f32 v1, v2, v3
	v_cvt_pk_bf16_f32 v2, v4, v5
	v_add_u32_e32 v4, v158, v159
	v_fma_f32 v6, v16, v6, v17
	v_fmac_f32_e32 v17, v16, v7
	v_cvt_pk_bf16_f32 v3, v6, v17
	ds_write_b128 v4, v[0:3]
	v_lshl_add_u64 v[0:1], v[142:143], 0, s[76:77]
	v_mov_b32_e32 v0, v210
	v_mov_b32_e32 v1, v211
	v_mov_b32_e32 v2, v212
	v_mov_b32_e32 v3, v213
	v_lshl_add_u64 v[4:5], v[92:93], 0, s[0:1]
	v_mov_b32_e32 v16, v28
	v_lshl_add_u64 v[4:5], v[94:95], 0, s[0:1]
	v_mov_b32_e32 v17, v29
	v_lshl_add_u64 v[142:143], v[142:143], 0, s[88:89]
	s_waitcnt vmcnt(2)
	v_lshlrev_b32_e32 v18, 16, v0
	v_and_b32_e32 v19, 0xffff0000, v0
	v_lshlrev_b32_e32 v20, 16, v1
	v_and_b32_e32 v21, 0xffff0000, v1
	v_lshlrev_b32_e32 v22, 16, v2
	v_and_b32_e32 v23, 0xffff0000, v2
	v_lshlrev_b32_e32 v24, 16, v3
	v_and_b32_e32 v25, 0xffff0000, v3
	ds_read_b128 v[0:3], v171
	ds_read_b128 v[4:7], v171 offset:16
	ds_read_b128 v[8:11], v171 offset:32
	ds_read_b128 v[12:15], v171 offset:48
	s_waitcnt lgkmcnt(3)
	v_sub_f32_e32 v0, v18, v0
	v_mul_f32_e32 v0, v1, v0
	v_sub_f32_e32 v1, v19, v2
	s_waitcnt lgkmcnt(2)
	v_sub_f32_e32 v2, v20, v4
	s_waitcnt lgkmcnt(1)
	v_sub_f32_e32 v4, v22, v8
	v_mul_f32_e32 v1, v3, v1
	v_mul_f32_e32 v2, v5, v2
	v_sub_f32_e32 v3, v21, v6
	v_mul_f32_e32 v4, v9, v4
	v_sub_f32_e32 v5, v23, v10
	s_waitcnt vmcnt(0)
	v_fma_f32 v0, v16, v0, v17
	v_fma_f32 v1, v16, v1, v17
	v_fma_f32 v2, v16, v2, v17
	v_mul_f32_e32 v3, v7, v3
	v_fma_f32 v4, v16, v4, v17
	v_mul_f32_e32 v5, v11, v5
	s_waitcnt lgkmcnt(0)
	v_sub_f32_e32 v6, v24, v12
	v_sub_f32_e32 v7, v25, v14
	v_fma_f32 v3, v16, v3, v17
	v_fma_f32 v5, v16, v5, v17
	v_mul_f32_e32 v6, v13, v6
	v_mul_f32_e32 v7, v15, v7
	v_cvt_pk_bf16_f32 v0, v0, v1
	v_cvt_pk_bf16_f32 v1, v2, v3
	v_cvt_pk_bf16_f32 v2, v4, v5
	v_add_u32_e32 v4, v158, v160
	v_fma_f32 v6, v16, v6, v17
	v_fmac_f32_e32 v17, v16, v7
	v_cvt_pk_bf16_f32 v3, v6, v17
	ds_write_b128 v4, v[0:3]
	v_lshl_add_u64 v[0:1], v[140:141], 0, s[76:77]
	v_mov_b32_e32 v0, v214
	v_mov_b32_e32 v1, v215
	v_mov_b32_e32 v2, v216
	v_mov_b32_e32 v3, v217
	v_lshl_add_u64 v[4:5], v[86:87], 0, s[0:1]
	v_mov_b32_e32 v16, v30
	v_lshl_add_u64 v[4:5], v[88:89], 0, s[0:1]
	v_mov_b32_e32 v17, v31
	v_lshl_add_u64 v[140:141], v[140:141], 0, s[88:89]
	s_waitcnt vmcnt(2)
	v_lshlrev_b32_e32 v18, 16, v0
	v_and_b32_e32 v19, 0xffff0000, v0
	v_lshlrev_b32_e32 v20, 16, v1
	v_and_b32_e32 v21, 0xffff0000, v1
	v_lshlrev_b32_e32 v22, 16, v2
	v_and_b32_e32 v23, 0xffff0000, v2
	v_lshlrev_b32_e32 v24, 16, v3
	v_and_b32_e32 v25, 0xffff0000, v3
	ds_read_b128 v[0:3], v171
	ds_read_b128 v[4:7], v171 offset:16
	ds_read_b128 v[8:11], v171 offset:32
	ds_read_b128 v[12:15], v171 offset:48
	s_waitcnt lgkmcnt(3)
	v_sub_f32_e32 v0, v18, v0
	v_mul_f32_e32 v0, v1, v0
	v_sub_f32_e32 v1, v19, v2
	s_waitcnt lgkmcnt(2)
	v_sub_f32_e32 v2, v20, v4
	s_waitcnt lgkmcnt(1)
	v_sub_f32_e32 v4, v22, v8
	v_mul_f32_e32 v1, v3, v1
	v_mul_f32_e32 v2, v5, v2
	v_sub_f32_e32 v3, v21, v6
	v_mul_f32_e32 v4, v9, v4
	v_sub_f32_e32 v5, v23, v10
	s_waitcnt vmcnt(0)
	v_fma_f32 v0, v16, v0, v17
	v_fma_f32 v1, v16, v1, v17
	v_fma_f32 v2, v16, v2, v17
	v_mul_f32_e32 v3, v7, v3
	v_fma_f32 v4, v16, v4, v17
	v_mul_f32_e32 v5, v11, v5
	s_waitcnt lgkmcnt(0)
	v_sub_f32_e32 v6, v24, v12
	v_sub_f32_e32 v7, v25, v14
	v_fma_f32 v3, v16, v3, v17
	v_fma_f32 v5, v16, v5, v17
	v_mul_f32_e32 v6, v13, v6
	v_mul_f32_e32 v7, v15, v7
	v_cvt_pk_bf16_f32 v0, v0, v1
	v_cvt_pk_bf16_f32 v1, v2, v3
	v_cvt_pk_bf16_f32 v2, v4, v5
	v_add_u32_e32 v4, v158, v161
	v_fma_f32 v6, v16, v6, v17
	v_fmac_f32_e32 v17, v16, v7
	v_cvt_pk_bf16_f32 v3, v6, v17
	ds_write_b128 v4, v[0:3]
	v_lshl_add_u64 v[0:1], v[138:139], 0, s[76:77]
	v_mov_b32_e32 v0, v218
	v_mov_b32_e32 v1, v219
	v_mov_b32_e32 v2, v220
	v_mov_b32_e32 v3, v221
	v_lshl_add_u64 v[4:5], v[80:81], 0, s[0:1]
	v_mov_b32_e32 v16, v238
	v_lshl_add_u64 v[4:5], v[82:83], 0, s[0:1]
	v_mov_b32_e32 v17, v239
	v_lshl_add_u64 v[138:139], v[138:139], 0, s[88:89]
	s_waitcnt vmcnt(2)
	v_lshlrev_b32_e32 v18, 16, v0
	v_and_b32_e32 v19, 0xffff0000, v0
	v_lshlrev_b32_e32 v20, 16, v1
	v_and_b32_e32 v21, 0xffff0000, v1
	v_lshlrev_b32_e32 v22, 16, v2
	v_and_b32_e32 v23, 0xffff0000, v2
	v_lshlrev_b32_e32 v24, 16, v3
	v_and_b32_e32 v25, 0xffff0000, v3
	ds_read_b128 v[0:3], v171
	ds_read_b128 v[4:7], v171 offset:16
	ds_read_b128 v[8:11], v171 offset:32
	ds_read_b128 v[12:15], v171 offset:48
	s_waitcnt lgkmcnt(3)
	v_sub_f32_e32 v0, v18, v0
	v_mul_f32_e32 v0, v1, v0
	v_sub_f32_e32 v1, v19, v2
	s_waitcnt lgkmcnt(2)
	v_sub_f32_e32 v2, v20, v4
	s_waitcnt lgkmcnt(1)
	v_sub_f32_e32 v4, v22, v8
	v_mul_f32_e32 v1, v3, v1
	v_mul_f32_e32 v2, v5, v2
	v_sub_f32_e32 v3, v21, v6
	v_mul_f32_e32 v4, v9, v4
	v_sub_f32_e32 v5, v23, v10
	s_waitcnt vmcnt(0)
	v_fma_f32 v0, v16, v0, v17
	v_fma_f32 v1, v16, v1, v17
	v_fma_f32 v2, v16, v2, v17
	v_mul_f32_e32 v3, v7, v3
	v_fma_f32 v4, v16, v4, v17
	v_mul_f32_e32 v5, v11, v5
	s_waitcnt lgkmcnt(0)
	v_sub_f32_e32 v6, v24, v12
	v_sub_f32_e32 v7, v25, v14
	v_fma_f32 v3, v16, v3, v17
	v_fma_f32 v5, v16, v5, v17
	v_mul_f32_e32 v6, v13, v6
	v_mul_f32_e32 v7, v15, v7
	v_cvt_pk_bf16_f32 v0, v0, v1
	v_cvt_pk_bf16_f32 v1, v2, v3
	v_cvt_pk_bf16_f32 v2, v4, v5
	v_add_u32_e32 v4, v158, v162
	v_fma_f32 v6, v16, v6, v17
	v_fmac_f32_e32 v17, v16, v7
	v_cvt_pk_bf16_f32 v3, v6, v17
	ds_write_b128 v4, v[0:3]
	v_lshl_add_u64 v[0:1], v[136:137], 0, s[76:77]
	v_mov_b32_e32 v0, v222
	v_mov_b32_e32 v1, v223
	v_mov_b32_e32 v2, v224
	v_mov_b32_e32 v3, v225
	v_lshl_add_u64 v[4:5], v[74:75], 0, s[0:1]
	v_mov_b32_e32 v16, v240
	v_lshl_add_u64 v[4:5], v[76:77], 0, s[0:1]
	v_mov_b32_e32 v17, v241
	v_lshl_add_u64 v[136:137], v[136:137], 0, s[88:89]
	s_waitcnt vmcnt(2)
	v_lshlrev_b32_e32 v18, 16, v0
	v_and_b32_e32 v19, 0xffff0000, v0
	v_lshlrev_b32_e32 v20, 16, v1
	v_and_b32_e32 v21, 0xffff0000, v1
	v_lshlrev_b32_e32 v22, 16, v2
	v_and_b32_e32 v23, 0xffff0000, v2
	v_lshlrev_b32_e32 v24, 16, v3
	v_and_b32_e32 v25, 0xffff0000, v3
	ds_read_b128 v[0:3], v171
	ds_read_b128 v[4:7], v171 offset:16
	ds_read_b128 v[8:11], v171 offset:32
	ds_read_b128 v[12:15], v171 offset:48
	s_waitcnt lgkmcnt(3)
	v_sub_f32_e32 v0, v18, v0
	v_mul_f32_e32 v0, v1, v0
	v_sub_f32_e32 v1, v19, v2
	v_mul_f32_e32 v1, v3, v1
	s_waitcnt lgkmcnt(2)
	v_sub_f32_e32 v2, v20, v4
	v_sub_f32_e32 v3, v21, v6
	s_waitcnt vmcnt(0)
	v_fma_f32 v0, v16, v0, v17
	v_fma_f32 v1, v16, v1, v17
	v_mul_f32_e32 v2, v5, v2
	v_mul_f32_e32 v3, v7, v3
	s_waitcnt lgkmcnt(1)
	v_sub_f32_e32 v4, v22, v8
	v_sub_f32_e32 v5, v23, v10
	s_waitcnt lgkmcnt(0)
	v_sub_f32_e32 v6, v24, v12
	v_sub_f32_e32 v7, v25, v14
	v_fma_f32 v2, v16, v2, v17
	v_fma_f32 v3, v16, v3, v17
	v_mul_f32_e32 v4, v9, v4
	v_mul_f32_e32 v5, v11, v5
	v_mul_f32_e32 v6, v13, v6
	v_mul_f32_e32 v7, v15, v7
	v_cvt_pk_bf16_f32 v0, v0, v1
	v_cvt_pk_bf16_f32 v1, v2, v3
	v_fma_f32 v4, v16, v4, v17
	v_fma_f32 v5, v16, v5, v17
	v_fma_f32 v6, v16, v6, v17
	v_fmac_f32_e32 v17, v16, v7
	v_cvt_pk_bf16_f32 v2, v4, v5
	v_cvt_pk_bf16_f32 v3, v6, v17
	ds_write_b128 v172, v[0:3]
	v_lshl_add_u64 v[0:1], v[134:135], 0, s[76:77]
	v_mov_b32_e32 v0, v226
	v_mov_b32_e32 v1, v227
	v_mov_b32_e32 v2, v228
	v_mov_b32_e32 v3, v229
	v_lshl_add_u64 v[4:5], v[68:69], 0, s[0:1]
	v_mov_b32_e32 v16, v247
	v_lshl_add_u64 v[4:5], v[70:71], 0, s[0:1]
	v_mov_b32_e32 v17, v248
	v_lshl_add_u64 v[134:135], v[134:135], 0, s[88:89]
	s_waitcnt vmcnt(2)
	v_lshlrev_b32_e32 v18, 16, v0
	v_and_b32_e32 v19, 0xffff0000, v0
	v_lshlrev_b32_e32 v20, 16, v1
	v_and_b32_e32 v21, 0xffff0000, v1
	v_lshlrev_b32_e32 v22, 16, v2
	v_and_b32_e32 v23, 0xffff0000, v2
	v_lshlrev_b32_e32 v24, 16, v3
	v_and_b32_e32 v25, 0xffff0000, v3
	ds_read_b128 v[0:3], v171
	ds_read_b128 v[4:7], v171 offset:16
	ds_read_b128 v[8:11], v171 offset:32
	ds_read_b128 v[12:15], v171 offset:48
	s_waitcnt lgkmcnt(3)
	v_sub_f32_e32 v0, v18, v0
	v_mul_f32_e32 v0, v1, v0
	v_sub_f32_e32 v1, v19, v2
	v_mul_f32_e32 v1, v3, v1
	s_waitcnt lgkmcnt(2)
	v_sub_f32_e32 v2, v20, v4
	v_sub_f32_e32 v3, v21, v6
	s_waitcnt vmcnt(0)
	v_fma_f32 v0, v16, v0, v17
	v_fma_f32 v1, v16, v1, v17
	v_mul_f32_e32 v2, v5, v2
	v_mul_f32_e32 v3, v7, v3
	s_waitcnt lgkmcnt(1)
	v_sub_f32_e32 v4, v22, v8
	v_sub_f32_e32 v5, v23, v10
	s_waitcnt lgkmcnt(0)
	v_sub_f32_e32 v6, v24, v12
	v_sub_f32_e32 v7, v25, v14
	v_fma_f32 v2, v16, v2, v17
	v_fma_f32 v3, v16, v3, v17
	v_mul_f32_e32 v4, v9, v4
	v_mul_f32_e32 v5, v11, v5
	v_mul_f32_e32 v6, v13, v6
	v_mul_f32_e32 v7, v15, v7
	v_cvt_pk_bf16_f32 v0, v0, v1
	v_cvt_pk_bf16_f32 v1, v2, v3
	v_fma_f32 v4, v16, v4, v17
	v_fma_f32 v5, v16, v5, v17
	v_fma_f32 v6, v16, v6, v17
	v_fmac_f32_e32 v17, v16, v7
	v_cvt_pk_bf16_f32 v2, v4, v5
	v_cvt_pk_bf16_f32 v3, v6, v17
	ds_write_b128 v173, v[0:3]
	v_lshl_add_u64 v[0:1], v[132:133], 0, s[76:77]
	v_mov_b32_e32 v0, v230
	v_mov_b32_e32 v1, v231
	v_mov_b32_e32 v2, v232
	v_mov_b32_e32 v3, v233
	v_lshl_add_u64 v[4:5], v[62:63], 0, s[0:1]
	v_mov_b32_e32 v16, v249
	v_lshl_add_u64 v[4:5], v[64:65], 0, s[0:1]
	v_mov_b32_e32 v17, v250
	v_lshl_add_u64 v[132:133], v[132:133], 0, s[88:89]
	s_waitcnt vmcnt(2)
	v_lshlrev_b32_e32 v18, 16, v0
	v_and_b32_e32 v19, 0xffff0000, v0
	v_lshlrev_b32_e32 v20, 16, v1
	v_and_b32_e32 v21, 0xffff0000, v1
	v_lshlrev_b32_e32 v22, 16, v2
	v_and_b32_e32 v23, 0xffff0000, v2
	v_lshlrev_b32_e32 v24, 16, v3
	v_and_b32_e32 v25, 0xffff0000, v3
	ds_read_b128 v[0:3], v171
	ds_read_b128 v[4:7], v171 offset:16
	ds_read_b128 v[8:11], v171 offset:32
	ds_read_b128 v[12:15], v171 offset:48
	s_waitcnt lgkmcnt(3)
	v_sub_f32_e32 v0, v18, v0
	v_mul_f32_e32 v0, v1, v0
	v_sub_f32_e32 v1, v19, v2
	v_mul_f32_e32 v1, v3, v1
	s_waitcnt lgkmcnt(2)
	v_sub_f32_e32 v2, v20, v4
	v_sub_f32_e32 v3, v21, v6
	s_waitcnt vmcnt(0)
	v_fma_f32 v0, v16, v0, v17
	v_fma_f32 v1, v16, v1, v17
	v_mul_f32_e32 v2, v5, v2
	v_mul_f32_e32 v3, v7, v3
	s_waitcnt lgkmcnt(1)
	v_sub_f32_e32 v4, v22, v8
	v_sub_f32_e32 v5, v23, v10
	s_waitcnt lgkmcnt(0)
	v_sub_f32_e32 v6, v24, v12
	v_sub_f32_e32 v7, v25, v14
	v_fma_f32 v2, v16, v2, v17
	v_fma_f32 v3, v16, v3, v17
	v_mul_f32_e32 v4, v9, v4
	v_mul_f32_e32 v5, v11, v5
	v_mul_f32_e32 v6, v13, v6
	v_mul_f32_e32 v7, v15, v7
	v_cvt_pk_bf16_f32 v0, v0, v1
	v_cvt_pk_bf16_f32 v1, v2, v3
	v_fma_f32 v4, v16, v4, v17
	v_fma_f32 v5, v16, v5, v17
	v_fma_f32 v6, v16, v6, v17
	v_fmac_f32_e32 v17, v16, v7
	v_cvt_pk_bf16_f32 v2, v4, v5
	v_cvt_pk_bf16_f32 v3, v6, v17
	ds_write_b128 v174, v[0:3]
	v_lshl_add_u64 v[0:1], v[130:131], 0, s[76:77]
	v_mov_b32_e32 v0, v234
	v_mov_b32_e32 v1, v235
	v_mov_b32_e32 v2, v236
	v_mov_b32_e32 v3, v237
	v_lshl_add_u64 v[4:5], v[56:57], 0, s[0:1]
	v_mov_b32_e32 v6, v251
	v_lshl_add_u64 v[4:5], v[58:59], 0, s[0:1]
	v_mov_b32_e32 v4, v252
	s_add_u32 s0, s0, 0x400
	s_addc_u32 s1, s1, 0
	v_lshl_add_u64 v[130:131], v[130:131], 0, s[88:89]
	s_cmpk_lg_i32 s0, 0x4000
	s_waitcnt vmcnt(2)
	v_lshlrev_b32_e32 v5, 16, v0
	v_and_b32_e32 v7, 0xffff0000, v0
	v_lshlrev_b32_e32 v20, 16, v1
	v_and_b32_e32 v21, 0xffff0000, v1
	v_lshlrev_b32_e32 v22, 16, v2
	v_and_b32_e32 v23, 0xffff0000, v2
	v_lshlrev_b32_e32 v24, 16, v3
	v_and_b32_e32 v25, 0xffff0000, v3
	ds_read_b128 v[0:3], v171
	ds_read_b128 v[8:11], v171 offset:16
	ds_read_b128 v[12:15], v171 offset:32
	ds_read_b128 v[16:19], v171 offset:48
	s_waitcnt lgkmcnt(3)
	v_sub_f32_e32 v0, v5, v0
	v_mul_f32_e32 v0, v1, v0
	v_sub_f32_e32 v1, v7, v2
	v_mul_f32_e32 v1, v3, v1
	s_waitcnt lgkmcnt(2)
	v_sub_f32_e32 v2, v20, v8
	v_sub_f32_e32 v3, v21, v10
	v_mul_f32_e32 v2, v9, v2
	v_mul_f32_e32 v3, v11, v3
	s_waitcnt lgkmcnt(1)
	v_sub_f32_e32 v5, v22, v12
	v_sub_f32_e32 v7, v23, v14
	s_waitcnt lgkmcnt(0)
	v_sub_f32_e32 v8, v24, v16
	v_sub_f32_e32 v9, v25, v18
	s_waitcnt vmcnt(0)
	v_fma_f32 v0, v6, v0, v4
	v_fma_f32 v1, v6, v1, v4
	v_fma_f32 v2, v6, v2, v4
	v_fma_f32 v3, v6, v3, v4
	v_mul_f32_e32 v5, v13, v5
	v_mul_f32_e32 v7, v15, v7
	v_mul_f32_e32 v8, v17, v8
	v_mul_f32_e32 v9, v19, v9
	v_fma_f32 v5, v6, v5, v4
	v_fma_f32 v7, v6, v7, v4
	v_fma_f32 v8, v6, v8, v4
	v_fmac_f32_e32 v4, v6, v9
	v_cvt_pk_bf16_f32 v0, v0, v1
	v_cvt_pk_bf16_f32 v1, v2, v3
	v_cvt_pk_bf16_f32 v2, v5, v7
	v_cvt_pk_bf16_f32 v3, v8, v4
	ds_write_b128 v175, v[0:3]
	s_waitcnt lgkmcnt(0)
	s_barrier
	ds_read_b128 v[16:19], v176
	ds_read_b128 v[20:23], v176 offset:4352
	ds_read_b128 v[0:3], v177
	s_waitcnt lgkmcnt(0)
	v_mfma_f32_16x16x32_bf16 v[12:15], v[16:19], v[0:3], 0
	ds_read_b128 v[24:27], v177 offset:8704
	v_mfma_f32_16x16x32_bf16 v[4:7], v[20:23], v[0:3], 0
	ds_read_b128 v[0:3], v177 offset:4352
	s_waitcnt lgkmcnt(1)
	v_mfma_f32_16x16x32_bf16 v[28:31], v[16:19], v[24:27], 0
	v_mfma_f32_16x16x32_bf16 v[180:183], v[20:23], v[24:27], 0
	ds_read_b128 v[24:27], v177 offset:13056
	s_waitcnt lgkmcnt(0)
	v_mfma_f32_16x16x32_bf16 v[188:191], v[16:19], v[24:27], 0
	v_mfma_f32_16x16x32_bf16 v[192:195], v[20:23], v[24:27], 0
	ds_read_b128 v[24:27], v177 offset:17408
	s_waitcnt lgkmcnt(0)
	v_mfma_f32_16x16x32_bf16 v[202:205], v[16:19], v[24:27], 0
	v_mfma_f32_16x16x32_bf16 v[206:209], v[20:23], v[24:27], 0
	ds_read_b128 v[24:27], v177 offset:21760
	s_waitcnt lgkmcnt(0)
	v_mfma_f32_16x16x32_bf16 v[210:213], v[16:19], v[24:27], 0
	v_mfma_f32_16x16x32_bf16 v[214:217], v[20:23], v[24:27], 0
	ds_read_b128 v[24:27], v177 offset:26112
	s_waitcnt lgkmcnt(0)
	v_mfma_f32_16x16x32_bf16 v[218:221], v[16:19], v[24:27], 0
	v_mfma_f32_16x16x32_bf16 v[222:225], v[20:23], v[24:27], 0
	ds_read_b128 v[24:27], v177 offset:30464
	v_mfma_f32_16x16x32_bf16 v[8:11], v[16:19], v[0:3], 0
	v_mfma_f32_16x16x32_bf16 v[0:3], v[20:23], v[0:3], 0
	s_waitcnt lgkmcnt(0)
	v_mfma_f32_16x16x32_bf16 v[226:229], v[16:19], v[24:27], 0
	ds_read_b128 v[234:237], v176 offset:64
	ds_read_b128 v[238:241], v176 offset:4416
	ds_read_b128 v[16:19], v177 offset:8768
	v_mfma_f32_16x16x32_bf16 v[230:233], v[20:23], v[24:27], 0
	ds_read_b128 v[20:23], v177 offset:13120
	s_waitcnt lgkmcnt(1)
	v_mfma_f32_16x16x32_bf16 v[24:27], v[234:237], v[16:19], v[28:31]
	v_mfma_f32_16x16x32_bf16 v[16:19], v[238:241], v[16:19], v[180:183]
	s_nop 2
	ds_read_b128 v[180:183], v177 offset:17472
	s_waitcnt lgkmcnt(1)
	v_mfma_f32_16x16x32_bf16 v[28:31], v[234:237], v[20:23], v[188:191]
	v_mfma_f32_16x16x32_bf16 v[20:23], v[238:241], v[20:23], v[192:195]
	s_nop 2
	ds_read_b128 v[192:195], v177 offset:21824
	s_waitcnt lgkmcnt(1)
	v_mfma_f32_16x16x32_bf16 v[188:191], v[234:237], v[180:183], v[202:205]
	v_mfma_f32_16x16x32_bf16 v[180:183], v[238:241], v[180:183], v[206:209]
	s_nop 2
	ds_read_b128 v[206:209], v177 offset:26176
	s_waitcnt lgkmcnt(1)
	v_mfma_f32_16x16x32_bf16 v[202:205], v[234:237], v[192:195], v[210:213]
	v_mfma_f32_16x16x32_bf16 v[192:195], v[238:241], v[192:195], v[214:217]
	s_nop 2
	ds_read_b128 v[214:217], v177 offset:30528
	s_waitcnt lgkmcnt(1)
	v_mfma_f32_16x16x32_bf16 v[210:213], v[234:237], v[206:209], v[218:221]
	v_mfma_f32_16x16x32_bf16 v[206:209], v[238:241], v[206:209], v[222:225]
	s_waitcnt lgkmcnt(0)
	v_mfma_f32_16x16x32_bf16 v[218:221], v[234:237], v[214:217], v[226:229]
	v_mfma_f32_16x16x32_bf16 v[214:217], v[238:241], v[214:217], v[230:233]
	ds_read_b128 v[222:225], v176 offset:128
	s_nop 0
	ds_read_b128 v[226:229], v176 offset:4480
	ds_read_b128 v[230:233], v177 offset:17536
	s_waitcnt lgkmcnt(0)
	v_mfma_f32_16x16x32_bf16 v[188:191], v[222:225], v[230:233], v[188:191]
	v_mfma_f32_16x16x32_bf16 v[180:183], v[226:229], v[230:233], v[180:183]
	ds_read_b128 v[230:233], v177 offset:21888
	s_waitcnt lgkmcnt(0)
	v_mfma_f32_16x16x32_bf16 v[202:205], v[222:225], v[230:233], v[202:205]
	v_mfma_f32_16x16x32_bf16 v[192:195], v[226:229], v[230:233], v[192:195]
	ds_read_b128 v[230:233], v177 offset:26240
	s_waitcnt lgkmcnt(0)
	v_mfma_f32_16x16x32_bf16 v[210:213], v[222:225], v[230:233], v[210:213]
	v_mfma_f32_16x16x32_bf16 v[206:209], v[226:229], v[230:233], v[206:209]
	ds_read_b128 v[230:233], v177 offset:30592
	s_waitcnt lgkmcnt(0)
	v_mfma_f32_16x16x32_bf16 v[218:221], v[222:225], v[230:233], v[218:221]
	v_mfma_f32_16x16x32_bf16 v[214:217], v[226:229], v[230:233], v[214:217]
	ds_read_b128 v[222:225], v176 offset:192
	ds_read_b128 v[226:229], v176 offset:4544
	ds_read_b128 v[230:233], v177 offset:26304
	s_waitcnt lgkmcnt(0)
	v_mfma_f32_16x16x32_bf16 v[210:213], v[222:225], v[230:233], v[210:213]
	v_mfma_f32_16x16x32_bf16 v[206:209], v[226:229], v[230:233], v[206:209]
	ds_read_b128 v[230:233], v178 offset:192
	s_waitcnt lgkmcnt(0)
	s_barrier
	v_mov_b32_e32 v187, v196
	v_mfma_f32_16x16x32_bf16 v[218:221], v[222:225], v[230:233], v[218:221]
	s_waitcnt vmcnt(0)
	v_add_f32_e32 v12, v12, v187
	v_add_f32_e32 v13, v13, v187
	v_cvt_pk_bf16_f32 v12, v12, v13
	v_add_f32_e32 v13, v14, v187
	v_add_f32_e32 v4, v4, v187
	v_add_f32_e32 v5, v5, v187
	v_add_f32_e32 v14, v15, v187
	v_cvt_pk_bf16_f32 v13, v13, v14
	ds_write_b64 v179, v[12:13]
	v_cvt_pk_bf16_f32 v4, v4, v5
	v_add_f32_e32 v5, v6, v187
	v_add_f32_e32 v6, v7, v187
	v_cvt_pk_bf16_f32 v5, v5, v6
	v_mov_b32_e32 v6, v197
	ds_write_b64 v179, v[4:5] offset:32
	v_mfma_f32_16x16x32_bf16 v[214:217], v[226:229], v[230:233], v[214:217]
	s_waitcnt vmcnt(0)
	v_add_f32_e32 v4, v8, v6
	v_add_f32_e32 v5, v9, v6
	v_cvt_pk_bf16_f32 v4, v4, v5
	v_add_f32_e32 v5, v10, v6
	v_add_f32_e32 v0, v0, v6
	v_add_f32_e32 v1, v1, v6
	v_add_f32_e32 v7, v11, v6
	v_cvt_pk_bf16_f32 v5, v5, v7
	ds_write_b64 v179, v[4:5] offset:8448
	v_cvt_pk_bf16_f32 v0, v0, v1
	v_add_f32_e32 v1, v2, v6
	v_add_f32_e32 v2, v3, v6
	v_cvt_pk_bf16_f32 v1, v1, v2
	v_mov_b32_e32 v2, v198
	ds_write_b64 v179, v[0:1] offset:8480
	v_lshl_add_u64 v[8:9], v[128:129], 0, s[76:77]
	v_lshl_add_u64 v[128:129], v[128:129], 0, s[88:89]
	s_waitcnt vmcnt(0)
	v_add_f32_e32 v0, v24, v2
	v_add_f32_e32 v1, v25, v2
	v_cvt_pk_bf16_f32 v0, v0, v1
	v_add_f32_e32 v1, v26, v2
	v_add_f32_e32 v3, v27, v2
	v_cvt_pk_bf16_f32 v1, v1, v3
	ds_write_b64 v179, v[0:1] offset:16896
	v_add_f32_e32 v0, v16, v2
	v_add_f32_e32 v1, v17, v2
	v_cvt_pk_bf16_f32 v0, v0, v1
	v_add_f32_e32 v1, v18, v2
	v_add_f32_e32 v2, v19, v2
	v_cvt_pk_bf16_f32 v1, v1, v2
	v_mov_b32_e32 v2, v201
	ds_write_b64 v179, v[0:1] offset:16928
	s_waitcnt vmcnt(0)
	v_add_f32_e32 v0, v28, v2
	v_add_f32_e32 v1, v29, v2
	v_cvt_pk_bf16_f32 v0, v0, v1
	v_add_f32_e32 v1, v30, v2
	v_add_f32_e32 v3, v31, v2
	v_cvt_pk_bf16_f32 v1, v1, v3
	ds_write_b64 v179, v[0:1] offset:25344
	v_add_f32_e32 v0, v20, v2
	v_add_f32_e32 v1, v21, v2
	v_cvt_pk_bf16_f32 v0, v0, v1
	v_add_f32_e32 v1, v22, v2
	v_add_f32_e32 v2, v23, v2
	v_cvt_pk_bf16_f32 v1, v1, v2
	v_mov_b32_e32 v2, v245
	ds_write_b64 v179, v[0:1] offset:25376
	s_waitcnt vmcnt(0)
	v_add_f32_e32 v0, v188, v2
	v_add_f32_e32 v1, v189, v2
	v_cvt_pk_bf16_f32 v0, v0, v1
	v_add_f32_e32 v1, v190, v2
	v_add_f32_e32 v3, v191, v2
	v_cvt_pk_bf16_f32 v1, v1, v3
	ds_write_b64 v179, v[0:1] offset:33792
	v_add_f32_e32 v0, v180, v2
	v_add_f32_e32 v1, v181, v2
	v_cvt_pk_bf16_f32 v0, v0, v1
	v_add_f32_e32 v1, v182, v2
	v_add_f32_e32 v2, v183, v2
	v_cvt_pk_bf16_f32 v1, v1, v2
	v_mov_b32_e32 v2, v246
	ds_write_b64 v179, v[0:1] offset:33824
	s_waitcnt vmcnt(0)
	v_add_f32_e32 v0, v202, v2
	v_add_f32_e32 v1, v203, v2
	v_cvt_pk_bf16_f32 v0, v0, v1
	v_add_f32_e32 v1, v204, v2
	v_add_f32_e32 v3, v205, v2
	v_cvt_pk_bf16_f32 v1, v1, v3
	ds_write_b64 v179, v[0:1] offset:42240
	v_add_f32_e32 v0, v192, v2
	v_add_f32_e32 v1, v193, v2
	v_cvt_pk_bf16_f32 v0, v0, v1
	v_add_f32_e32 v1, v194, v2
	v_add_f32_e32 v2, v195, v2
	v_cvt_pk_bf16_f32 v1, v1, v2
	v_mov_b32_e32 v2, v253
	ds_write_b64 v179, v[0:1] offset:42272
	s_waitcnt vmcnt(0)
	v_add_f32_e32 v0, v210, v2
	v_add_f32_e32 v1, v211, v2
	v_cvt_pk_bf16_f32 v0, v0, v1
	v_add_f32_e32 v1, v212, v2
	v_add_f32_e32 v3, v213, v2
	v_cvt_pk_bf16_f32 v1, v1, v3
	ds_write_b64 v179, v[0:1] offset:50688
	v_add_f32_e32 v0, v206, v2
	v_add_f32_e32 v1, v207, v2
	v_cvt_pk_bf16_f32 v0, v0, v1
	v_add_f32_e32 v1, v208, v2
	v_add_f32_e32 v2, v209, v2
	v_cvt_pk_bf16_f32 v1, v1, v2
	v_mov_b32_e32 v2, v254
	ds_write_b64 v179, v[0:1] offset:50720
	v_lshl_add_u64 v[152:153], v[152:153], 0, s[2:3]
	s_waitcnt vmcnt(0)
	v_add_f32_e32 v0, v218, v2
	v_add_f32_e32 v1, v219, v2
	v_cvt_pk_bf16_f32 v0, v0, v1
	v_add_f32_e32 v1, v220, v2
	v_add_f32_e32 v3, v221, v2
	v_cvt_pk_bf16_f32 v1, v1, v3
	ds_write_b64 v179, v[0:1] offset:59136
	v_add_f32_e32 v0, v214, v2
	v_add_f32_e32 v1, v215, v2
	v_cvt_pk_bf16_f32 v0, v0, v1
	v_add_f32_e32 v1, v216, v2
	v_add_f32_e32 v2, v217, v2
	v_cvt_pk_bf16_f32 v1, v1, v2
	ds_write_b64 v179, v[0:1] offset:59168
	s_waitcnt lgkmcnt(0)
	s_barrier
	global_load_dwordx4 v[12:15], v[8:9], off
	v_lshl_add_u64 v[0:1], v[126:127], 0, s[76:77]
	global_load_dwordx4 v[16:19], v[0:1], off
	v_lshl_add_u64 v[0:1], v[124:125], 0, s[76:77]
	global_load_dwordx4 v[20:23], v[0:1], off
	v_lshl_add_u64 v[0:1], v[122:123], 0, s[76:77]
	global_load_dwordx4 v[24:27], v[0:1], off
	v_lshl_add_u64 v[0:1], v[120:121], 0, s[76:77]
	global_load_dwordx4 v[28:31], v[0:1], off
	v_lshl_add_u64 v[0:1], v[118:119], 0, s[76:77]
	global_load_dwordx4 v[180:183], v[0:1], off
	v_lshl_add_u64 v[0:1], v[116:117], 0, s[76:77]
	global_load_dwordx4 v[188:191], v[0:1], off
	v_lshl_add_u64 v[0:1], v[114:115], 0, s[76:77]
	global_load_dwordx4 v[192:195], v[0:1], off
	s_waitcnt vmcnt(0)
	v_mov_b32_e32 v0, v12
	v_mov_b32_e32 v1, v13
	v_mov_b32_e32 v2, v14
	v_mov_b32_e32 v3, v15
	ds_read_b128 v[4:7], v163
	s_waitcnt lgkmcnt(0)
	v_lshlrev_b32_e32 v11, 16, v4
	v_and_b32_e32 v4, 0xffff0000, v4
	v_lshlrev_b32_e32 v10, 16, v0
	v_and_b32_e32 v0, 0xffff0000, v0
	v_mul_f32_e32 v10, v11, v10
	v_mul_f32_e32 v0, v4, v0
	v_cvt_pk_bf16_f32 v0, v10, v0
	v_lshlrev_b32_e32 v4, 16, v1
	v_lshlrev_b32_e32 v10, 16, v5
	v_and_b32_e32 v5, 0xffff0000, v5
	v_and_b32_e32 v1, 0xffff0000, v1
	v_mul_f32_e32 v4, v10, v4
	v_mul_f32_e32 v1, v5, v1
	v_cvt_pk_bf16_f32 v1, v4, v1
	v_lshlrev_b32_e32 v4, 16, v2
	v_lshlrev_b32_e32 v5, 16, v6
	v_mul_f32_e32 v4, v5, v4
	v_and_b32_e32 v5, 0xffff0000, v6
	v_and_b32_e32 v2, 0xffff0000, v2
	v_mul_f32_e32 v2, v5, v2
	v_cvt_pk_bf16_f32 v2, v4, v2
	v_lshlrev_b32_e32 v4, 16, v3
	v_lshlrev_b32_e32 v5, 16, v7
	v_mul_f32_e32 v4, v5, v4
	v_and_b32_e32 v5, 0xffff0000, v7
	v_and_b32_e32 v3, 0xffff0000, v3
	v_mul_f32_e32 v3, v5, v3
	v_cvt_pk_bf16_f32 v3, v4, v3
	global_store_dwordx4 v[8:9], v[0:3], off
	s_nop 1
	v_lshl_add_u64 v[8:9], v[126:127], 0, s[76:77]
	v_mov_b32_e32 v0, v16
	v_mov_b32_e32 v1, v17
	v_mov_b32_e32 v2, v18
	v_mov_b32_e32 v3, v19
	ds_read_b128 v[4:7], v164
	v_lshl_add_u64 v[126:127], v[126:127], 0, s[88:89]
	s_waitcnt lgkmcnt(0)
	v_lshlrev_b32_e32 v10, 16, v4
	v_and_b32_e32 v4, 0xffff0000, v4
	v_lshlrev_b32_e32 v11, 16, v0
	v_and_b32_e32 v0, 0xffff0000, v0
	v_mul_f32_e32 v10, v10, v11
	v_mul_f32_e32 v0, v4, v0
	v_cvt_pk_bf16_f32 v0, v10, v0
	v_lshlrev_b32_e32 v4, 16, v5
	v_lshlrev_b32_e32 v10, 16, v1
	v_and_b32_e32 v5, 0xffff0000, v5
	v_and_b32_e32 v1, 0xffff0000, v1
	v_mul_f32_e32 v4, v4, v10
	v_mul_f32_e32 v1, v5, v1
	v_cvt_pk_bf16_f32 v1, v4, v1
	v_lshlrev_b32_e32 v4, 16, v6
	v_lshlrev_b32_e32 v5, 16, v2
	v_mul_f32_e32 v4, v4, v5
	v_and_b32_e32 v5, 0xffff0000, v6
	v_and_b32_e32 v2, 0xffff0000, v2
	v_mul_f32_e32 v2, v5, v2
	v_cvt_pk_bf16_f32 v2, v4, v2
	v_lshlrev_b32_e32 v4, 16, v7
	v_lshlrev_b32_e32 v5, 16, v3
	v_mul_f32_e32 v4, v4, v5
	v_and_b32_e32 v5, 0xffff0000, v7
	v_and_b32_e32 v3, 0xffff0000, v3
	v_mul_f32_e32 v3, v5, v3
	v_cvt_pk_bf16_f32 v3, v4, v3
	global_store_dwordx4 v[8:9], v[0:3], off
	s_nop 1
	v_lshl_add_u64 v[8:9], v[124:125], 0, s[76:77]
	v_mov_b32_e32 v0, v20
	v_mov_b32_e32 v1, v21
	v_mov_b32_e32 v2, v22
	v_mov_b32_e32 v3, v23
	ds_read_b128 v[4:7], v165
	v_lshl_add_u64 v[124:125], v[124:125], 0, s[88:89]
	s_waitcnt lgkmcnt(0)
	v_lshlrev_b32_e32 v10, 16, v4
	v_and_b32_e32 v4, 0xffff0000, v4
	v_lshlrev_b32_e32 v11, 16, v0
	v_and_b32_e32 v0, 0xffff0000, v0
	v_mul_f32_e32 v10, v10, v11
	v_mul_f32_e32 v0, v4, v0
	v_cvt_pk_bf16_f32 v0, v10, v0
	v_lshlrev_b32_e32 v4, 16, v5
	v_lshlrev_b32_e32 v10, 16, v1
	v_and_b32_e32 v5, 0xffff0000, v5
	v_and_b32_e32 v1, 0xffff0000, v1
	v_mul_f32_e32 v4, v4, v10
	v_mul_f32_e32 v1, v5, v1
	v_cvt_pk_bf16_f32 v1, v4, v1
	v_lshlrev_b32_e32 v4, 16, v6
	v_lshlrev_b32_e32 v5, 16, v2
	v_mul_f32_e32 v4, v4, v5
	v_and_b32_e32 v5, 0xffff0000, v6
	v_and_b32_e32 v2, 0xffff0000, v2
	v_mul_f32_e32 v2, v5, v2
	v_cvt_pk_bf16_f32 v2, v4, v2
	v_lshlrev_b32_e32 v4, 16, v7
	v_lshlrev_b32_e32 v5, 16, v3
	v_mul_f32_e32 v4, v4, v5
	v_and_b32_e32 v5, 0xffff0000, v7
	v_and_b32_e32 v3, 0xffff0000, v3
	v_mul_f32_e32 v3, v5, v3
	v_cvt_pk_bf16_f32 v3, v4, v3
	global_store_dwordx4 v[8:9], v[0:3], off
	s_nop 1
	v_lshl_add_u64 v[8:9], v[122:123], 0, s[76:77]
	v_mov_b32_e32 v0, v24
	v_mov_b32_e32 v1, v25
	v_mov_b32_e32 v2, v26
	v_mov_b32_e32 v3, v27
	ds_read_b128 v[4:7], v166
	v_lshl_add_u64 v[122:123], v[122:123], 0, s[88:89]
	s_waitcnt lgkmcnt(0)
	v_lshlrev_b32_e32 v10, 16, v4
	v_and_b32_e32 v4, 0xffff0000, v4
	v_lshlrev_b32_e32 v11, 16, v0
	v_and_b32_e32 v0, 0xffff0000, v0
	v_mul_f32_e32 v10, v10, v11
	v_mul_f32_e32 v0, v4, v0
	v_cvt_pk_bf16_f32 v0, v10, v0
	v_lshlrev_b32_e32 v4, 16, v5
	v_lshlrev_b32_e32 v10, 16, v1
	v_and_b32_e32 v5, 0xffff0000, v5
	v_and_b32_e32 v1, 0xffff0000, v1
	v_mul_f32_e32 v4, v4, v10
	v_mul_f32_e32 v1, v5, v1
	v_cvt_pk_bf16_f32 v1, v4, v1
	v_lshlrev_b32_e32 v4, 16, v6
	v_lshlrev_b32_e32 v5, 16, v2
	v_mul_f32_e32 v4, v4, v5
	v_and_b32_e32 v5, 0xffff0000, v6
	v_and_b32_e32 v2, 0xffff0000, v2
	v_mul_f32_e32 v2, v5, v2
	v_cvt_pk_bf16_f32 v2, v4, v2
	v_lshlrev_b32_e32 v4, 16, v7
	v_lshlrev_b32_e32 v5, 16, v3
	v_mul_f32_e32 v4, v4, v5
	v_and_b32_e32 v5, 0xffff0000, v7
	v_and_b32_e32 v3, 0xffff0000, v3
	v_mul_f32_e32 v3, v5, v3
	v_cvt_pk_bf16_f32 v3, v4, v3
	global_store_dwordx4 v[8:9], v[0:3], off
	s_nop 1
	v_lshl_add_u64 v[8:9], v[120:121], 0, s[76:77]
	v_mov_b32_e32 v0, v28
	v_mov_b32_e32 v1, v29
	v_mov_b32_e32 v2, v30
	v_mov_b32_e32 v3, v31
	ds_read_b128 v[4:7], v167
	v_lshl_add_u64 v[120:121], v[120:121], 0, s[88:89]
	s_waitcnt lgkmcnt(0)
	v_lshlrev_b32_e32 v10, 16, v4
	v_and_b32_e32 v4, 0xffff0000, v4
	v_lshlrev_b32_e32 v11, 16, v0
	v_and_b32_e32 v0, 0xffff0000, v0
	v_mul_f32_e32 v10, v10, v11
	v_mul_f32_e32 v0, v4, v0
	v_cvt_pk_bf16_f32 v0, v10, v0
	v_lshlrev_b32_e32 v4, 16, v5
	v_lshlrev_b32_e32 v10, 16, v1
	v_and_b32_e32 v5, 0xffff0000, v5
	v_and_b32_e32 v1, 0xffff0000, v1
	v_mul_f32_e32 v4, v4, v10
	v_mul_f32_e32 v1, v5, v1
	v_cvt_pk_bf16_f32 v1, v4, v1
	v_lshlrev_b32_e32 v4, 16, v6
	v_lshlrev_b32_e32 v5, 16, v2
	v_mul_f32_e32 v4, v4, v5
	v_and_b32_e32 v5, 0xffff0000, v6
	v_and_b32_e32 v2, 0xffff0000, v2
	v_mul_f32_e32 v2, v5, v2
	v_cvt_pk_bf16_f32 v2, v4, v2
	v_lshlrev_b32_e32 v4, 16, v7
	v_lshlrev_b32_e32 v5, 16, v3
	v_mul_f32_e32 v4, v4, v5
	v_and_b32_e32 v5, 0xffff0000, v7
	v_and_b32_e32 v3, 0xffff0000, v3
	v_mul_f32_e32 v3, v5, v3
	v_cvt_pk_bf16_f32 v3, v4, v3
	global_store_dwordx4 v[8:9], v[0:3], off
	s_nop 1
	ds_read_b128 v[6:9], v168
	s_waitcnt lgkmcnt(0)
	v_lshlrev_b32_e32 v10, 16, v6
	v_lshl_add_u64 v[0:1], v[118:119], 0, s[76:77]
	v_mov_b32_e32 v2, v180
	v_mov_b32_e32 v3, v181
	v_mov_b32_e32 v4, v182
	v_mov_b32_e32 v5, v183
	v_and_b32_e32 v6, 0xffff0000, v6
	v_lshl_add_u64 v[118:119], v[118:119], 0, s[88:89]
	v_lshlrev_b32_e32 v11, 16, v2
	v_and_b32_e32 v2, 0xffff0000, v2
	v_mul_f32_e32 v10, v10, v11
	v_mul_f32_e32 v2, v6, v2
	v_cvt_pk_bf16_f32 v2, v10, v2
	v_lshlrev_b32_e32 v6, 16, v7
	v_lshlrev_b32_e32 v10, 16, v3
	v_and_b32_e32 v7, 0xffff0000, v7
	v_and_b32_e32 v3, 0xffff0000, v3
	v_mul_f32_e32 v6, v6, v10
	v_mul_f32_e32 v3, v7, v3
	v_cvt_pk_bf16_f32 v3, v6, v3
	v_lshlrev_b32_e32 v6, 16, v8
	v_lshlrev_b32_e32 v7, 16, v4
	v_mul_f32_e32 v6, v6, v7
	v_and_b32_e32 v7, 0xffff0000, v8
	v_and_b32_e32 v4, 0xffff0000, v4
	v_mul_f32_e32 v4, v7, v4
	v_cvt_pk_bf16_f32 v4, v6, v4
	v_lshlrev_b32_e32 v6, 16, v9
	v_lshlrev_b32_e32 v7, 16, v5
	v_mul_f32_e32 v6, v6, v7
	v_and_b32_e32 v7, 0xffff0000, v9
	v_and_b32_e32 v5, 0xffff0000, v5
	v_mul_f32_e32 v5, v7, v5
	v_cvt_pk_bf16_f32 v5, v6, v5
	global_store_dwordx4 v[0:1], v[2:5], off
	s_nop 1
	v_lshl_add_u64 v[8:9], v[116:117], 0, s[76:77]
	v_mov_b32_e32 v0, v188
	v_mov_b32_e32 v1, v189
	v_mov_b32_e32 v2, v190
	v_mov_b32_e32 v3, v191
	ds_read_b128 v[4:7], v169
	v_lshl_add_u64 v[116:117], v[116:117], 0, s[88:89]
	s_waitcnt lgkmcnt(0)
	v_lshlrev_b32_e32 v10, 16, v4
	v_and_b32_e32 v4, 0xffff0000, v4
	v_lshlrev_b32_e32 v11, 16, v0
	v_and_b32_e32 v0, 0xffff0000, v0
	v_mul_f32_e32 v10, v10, v11
	v_mul_f32_e32 v0, v4, v0
	v_cvt_pk_bf16_f32 v0, v10, v0
	v_lshlrev_b32_e32 v4, 16, v5
	v_lshlrev_b32_e32 v10, 16, v1
	v_and_b32_e32 v5, 0xffff0000, v5
	v_and_b32_e32 v1, 0xffff0000, v1
	v_mul_f32_e32 v4, v4, v10
	v_mul_f32_e32 v1, v5, v1
	v_cvt_pk_bf16_f32 v1, v4, v1
	v_lshlrev_b32_e32 v4, 16, v6
	v_lshlrev_b32_e32 v5, 16, v2
	v_mul_f32_e32 v4, v4, v5
	v_and_b32_e32 v5, 0xffff0000, v6
	v_and_b32_e32 v2, 0xffff0000, v2
	v_mul_f32_e32 v2, v5, v2
	v_cvt_pk_bf16_f32 v2, v4, v2
	v_lshlrev_b32_e32 v4, 16, v7
	v_lshlrev_b32_e32 v5, 16, v3
	v_mul_f32_e32 v4, v4, v5
	v_and_b32_e32 v5, 0xffff0000, v7
	v_and_b32_e32 v3, 0xffff0000, v3
	v_mul_f32_e32 v3, v5, v3
	v_cvt_pk_bf16_f32 v3, v4, v3
	global_store_dwordx4 v[8:9], v[0:3], off
	s_nop 1
	v_lshl_add_u64 v[8:9], v[114:115], 0, s[76:77]
	v_mov_b32_e32 v0, v192
	v_mov_b32_e32 v1, v193
	v_mov_b32_e32 v2, v194
	v_mov_b32_e32 v3, v195
	ds_read_b128 v[4:7], v170
	v_lshl_add_u64 v[114:115], v[114:115], 0, s[88:89]
	s_waitcnt lgkmcnt(0)
	v_lshlrev_b32_e32 v10, 16, v4
	v_and_b32_e32 v4, 0xffff0000, v4
	v_lshlrev_b32_e32 v11, 16, v0
	v_and_b32_e32 v0, 0xffff0000, v0
	v_mul_f32_e32 v10, v10, v11
	v_mul_f32_e32 v0, v4, v0
	v_cvt_pk_bf16_f32 v0, v10, v0
	v_lshlrev_b32_e32 v4, 16, v5
	v_lshlrev_b32_e32 v10, 16, v1
	v_and_b32_e32 v5, 0xffff0000, v5
	v_and_b32_e32 v1, 0xffff0000, v1
	v_mul_f32_e32 v4, v4, v10
	v_mul_f32_e32 v1, v5, v1
	v_cvt_pk_bf16_f32 v1, v4, v1
	v_lshlrev_b32_e32 v4, 16, v6
	v_lshlrev_b32_e32 v5, 16, v2
	v_mul_f32_e32 v4, v4, v5
	v_and_b32_e32 v5, 0xffff0000, v6
	v_and_b32_e32 v2, 0xffff0000, v2
	v_mul_f32_e32 v2, v5, v2
	v_cvt_pk_bf16_f32 v2, v4, v2
	v_lshlrev_b32_e32 v4, 16, v7
	v_lshlrev_b32_e32 v5, 16, v3
	v_mul_f32_e32 v4, v4, v5
	v_and_b32_e32 v5, 0xffff0000, v7
	v_and_b32_e32 v3, 0xffff0000, v3
	v_mul_f32_e32 v3, v5, v3
	v_cvt_pk_bf16_f32 v3, v4, v3
	global_store_dwordx4 v[8:9], v[0:3], off
	s_nop 1
	s_barrier
	s_cbranch_scc1 .LBB0_296
	s_load_dword s0, s[68:69], 0x0
	s_waitcnt lgkmcnt(0)
	s_add_i32 s12, s0, s12
	s_cmpk_gt_i32 s12, 0xff
	s_cbranch_scc0 .LBB0_293
